# attention: block index permuted so one XCD's 32 workgroups process 32 consecutive items (shared key/value blocks hit that XCD's L2)
# speedup vs baseline: 1.0024x; 1.0024x over previous
; __device__ __forceinline__ void p4_attn(const Params& p, LAS unsigned char* lds, const int dummy) {
;     ...
;     int it = blockIdx.x;
;     if (it < 1536) { const AttnItem a0 = attn_item(it); attn_load(R1, a0, tid, kr, vr); }
;     for (; it < 1536; it += gridDim.x) {
.LBB0_570:
	v_writelane_b32 v254, s84, 63
	s_cmpk_lg_i32 s82, 0x100
	s_cbranch_scc1 .Lattn_perm_done
	s_and_b32 s100, s84, 7
	s_lshl_b32 s100, s100, 5
	s_lshr_b32 s84, s84, 3
	s_or_b32 s84, s84, s100

; __device__ __forceinline__ void xcd_barrier(const XcdBarrier& b) {
;     asm volatile("s_waitcnt vmcnt(0)" ::: "memory");
;     __syncthreads();
;     if (threadIdx.x == 0) {
;         unsigned* bar = b.bar;
;         __builtin_amdgcn_s_waitcnt(0);
;         unsigned nloc = b.st[0], nx = b.st[1];
;         if (nloc == 0u) { xcd_barrier_complete(bar, b.x, nloc, nx); b.st[0] = nloc; b.st[1] = nx; }
.LBB0_629:
	v_readlane_b32 s84, v254, 63
	s_nop 3
	v_writelane_b32 v254, s84, 54
	s_setprio 0
	s_cmp_gt_i32 s91, 6
	s_cselect_b64 s[0:1], -1, 0
	s_and_b64 s[2:3], s[96:97], s[0:1]
	s_andn2_b64 vcc, exec, s[2:3]
	s_cbranch_vccnz .LBB0_679
	s_waitcnt vmcnt(0)
	s_waitcnt vmcnt(0) lgkmcnt(0)
	s_barrier
	s_mov_b64 s[2:3], exec
	v_readlane_b32 s4, v254, 1
	v_readlane_b32 s5, v254, 2
	s_and_b64 s[4:5], s[2:3], s[4:5]
	s_mov_b64 exec, s[4:5]
	s_cbranch_execz .LBB0_678
	v_readlane_b32 s4, v254, 22
	s_waitcnt vmcnt(0) expcnt(0) lgkmcnt(0)
	s_nop 0
	v_mov_b32_e32 v0, s4
	ds_read_b32 v2, v0
	ds_read_b32 v0, v0 offset:4
	s_waitcnt lgkmcnt(1)
	v_cmp_ne_u32_e32 vcc, 0, v2
	s_cbranch_vccnz .LBB0_646
	v_readlane_b32 s4, v254, 0
	s_mul_i32 s33, s83, s4
	s_add_u32 s4, s88, 0xffc0200
	s_addc_u32 s5, s89, 0
	s_add_u32 s6, s88, 0xffc0400
	s_addc_u32 s7, s89, 0
	s_add_u32 s8, s88, 0xffc0500
	s_addc_u32 s9, s89, 0
	s_add_u32 s10, s88, 0xffc0600
	s_addc_u32 s11, s89, 0
	s_add_u32 s12, s88, 0xffc0700
	s_addc_u32 s13, s89, 0
	s_add_u32 s14, s88, 0xffc0800
	s_addc_u32 s15, s89, 0
	s_add_u32 s16, s88, 0xffc0900
	s_addc_u32 s17, s89, 0
	s_add_u32 s18, s88, 0xffc0a00
	s_addc_u32 s19, s89, 0
	s_add_u32 s20, s88, 0xffc0b00
	s_addc_u32 s21, s89, 0
	s_add_u32 s22, s88, 0xffc0c00
	s_addc_u32 s23, s89, 0
	s_add_u32 s24, s88, 0xffc0d00
	s_addc_u32 s25, s89, 0
	s_add_u32 s26, s88, 0xffc0e00
	s_addc_u32 s27, s89, 0
	s_add_u32 s28, s88, 0xffc0f00
	s_addc_u32 s29, s89, 0
	s_add_u32 s30, s88, 0xffc1000
	s_addc_u32 s31, s89, 0
	s_add_u32 s34, s88, 0xffc1100
	s_addc_u32 s35, s89, 0
	s_add_u32 s36, s88, 0xffc1200
	s_addc_u32 s37, s89, 0
	s_add_u32 s38, s88, 0xffc1300
	s_mul_i32 s33, s33, s82
	s_addc_u32 s39, s89, 0
	s_mov_b32 s46, 1
	v_mov_b32_e32 v16, 0
	s_branch .LBB0_634
